# GU K-loop: stage DMAs use the scalar-base + 32-bit lane offset form, removing 16 VALU 64-bit address adds per wave per K-iteration
# baseline (speedup 1.0000x reference)
; #define PG8_STAGE(bufoff, gbase, voff) do { _Pragma("unroll") for (int _i = 0; _i < 2; ++_i) \
;         __builtin_amdgcn_global_load_lds((const unsigned*)((const char*)(gbase) + (voff)[_i]), (LAS unsigned*)(lds + (bufoff) + ldsw + _i * 8192), 16, 0, 0); } while (0)
; #define PG8_LDA(dst, b, h) do { _Pragma("unroll") for (int m = 0; m < 4; ++m) _Pragma("unroll") for (int k = 0; k < 2; ++k) dst[m][k] = *(const LAS bf16x8*)(lds + PG8_SA(b, h) + aoff + m * 2048 + k * 1024); } while (0)
; #define PG8_LDB(dst, b, h) do { _Pragma("unroll") for (int n = 0; n < 2; ++n) _Pragma("unroll") for (int k = 0; k < 2; ++k) dst[n][k] = *(const LAS bf16x8*)(lds + PG8_SB(b, h) + boff + n * 2048 + k * 1024); } while (0)
; #define PG8_MMA(ai, bj, At, Bt) do { __builtin_amdgcn_s_setprio(1); _Pragma("unroll") for (int m = 0; m < 4; ++m) _Pragma("unroll") for (int n = 0; n < 2; ++n) _Pragma("unroll") for (int k = 0; k < 2; ++k) \
;         acc[ai][bj][m][n] = __builtin_amdgcn_mfma_f32_16x16x32_bf16(Bt[n][k], At[m][k], acc[ai][bj][m][n], 0, 0, 0); __builtin_amdgcn_s_setprio(0); } while (0)
; #define PG8_WAIT_V(n) asm volatile("s_waitcnt vmcnt(" #n ")" ::: "memory")
; #define PG8_WAIT_L(n) asm volatile("s_waitcnt lgkmcnt(" #n ")" ::: "memory")
; #define PG8_BAR __builtin_amdgcn_s_barrier()
; #define PG8_SCHED __builtin_amdgcn_sched_barrier(0)
; template <class Epi, bool ALIGN_EPI>
; __device__ __forceinline__ void gemm_phase(LAS unsigned char* lds, const Gemm g, int G, int cid, const Epi& E) {
;     ...
;             PG8_LDB(B0, 0, 0); PG8_LDB(B1, 0, 1); PG8_SCHED; PG8_LDA(At, 0, 0); PG8_STAGE(PG8_SA(1, 1), a1 + hA, voffA);
;             PG8_WAIT_V(8); PG8_WAIT_L(0); PG8_BAR; PG8_MMA(0, 0, At, B0); PG8_MMA(0, 1, At, B1); PG8_BAR; PG8_SCHED;
;             PG8_LDA(At, 0, 1); PG8_STAGE(PG8_SB(0, 0), b2, voffB); PG8_STAGE(PG8_SB(0, 1), b2 + hB, voffB); PG8_STAGE(PG8_SA(0, 0), a2, voffA);
;             PG8_WAIT_V(8); PG8_WAIT_L(0); PG8_BAR; PG8_MMA(1, 0, At, B0); PG8_MMA(1, 1, At, B1); PG8_BAR; PG8_SCHED;
.LBB0_813:
	s_add_u32 s54, s52, 0x100
	s_addc_u32 s55, s53, 0
	s_and_b64 s[6:7], exec, s[58:59]
	s_cselect_b32 s59, s45, s55
	s_cselect_b32 s58, s44, s54
	s_add_i32 s6, 0, 0x10000
	s_add_i32 s92, 0, 0x14000
	v_add_u32_e32 v144, s6, v176
	v_add_u32_e32 v160, s92, v176
	ds_read_b128 v[128:131], v144
	ds_read_b128 v[132:135], v144 offset:1024
	ds_read_b128 v[140:143], v144 offset:2048
	ds_read_b128 v[144:147], v144 offset:3072
	ds_read_b128 v[148:151], v160
	ds_read_b128 v[152:155], v160 offset:1024
	ds_read_b128 v[156:159], v160 offset:2048
	ds_read_b128 v[160:163], v160 offset:3072
	s_add_i32 m0, s13, 0xc000
	ds_read_b128 v[180:183], v179
	ds_read_b128 v[184:187], v179 offset:1024
	ds_read_b128 v[188:191], v179 offset:2048
	ds_read_b128 v[206:209], v179 offset:3072
	ds_read_b128 v[210:213], v179 offset:4096
	ds_read_b128 v[214:217], v179 offset:5120
	ds_read_b128 v[218:221], v179 offset:6144
	ds_read_b128 v[222:225], v179 offset:7168
	global_load_lds_dwordx4 v170, s[52:53]
	s_add_i32 m0, s13, 0xe000
	s_nop 0
	global_load_lds_dwordx4 v172, s[52:53]
	s_waitcnt vmcnt(8)
	s_waitcnt lgkmcnt(0)
	s_barrier
	s_setprio 1
	s_waitcnt lgkmcnt(0)
	v_mfma_f32_16x16x32_bf16 v[124:127], v[128:131], v[180:183], v[124:127]
	v_mfma_f32_16x16x32_bf16 v[120:123], v[140:143], v[180:183], v[120:123]
	v_mfma_f32_16x16x32_bf16 v[108:111], v[128:131], v[188:191], v[108:111]
	v_mfma_f32_16x16x32_bf16 v[104:107], v[140:143], v[188:191], v[104:107]
	v_mfma_f32_16x16x32_bf16 v[92:95], v[128:131], v[210:213], v[92:95]
	v_mfma_f32_16x16x32_bf16 v[88:91], v[140:143], v[210:213], v[88:91]
	v_mfma_f32_16x16x32_bf16 v[76:79], v[128:131], v[218:221], v[76:79]
	v_mfma_f32_16x16x32_bf16 v[72:75], v[140:143], v[218:221], v[72:75]
	v_mfma_f32_16x16x32_bf16 v[124:127], v[132:135], v[184:187], v[124:127]
	v_mfma_f32_16x16x32_bf16 v[120:123], v[144:147], v[184:187], v[120:123]
	v_mfma_f32_16x16x32_bf16 v[108:111], v[132:135], v[206:209], v[108:111]
	v_mfma_f32_16x16x32_bf16 v[104:107], v[144:147], v[206:209], v[104:107]
	v_mfma_f32_16x16x32_bf16 v[92:95], v[132:135], v[214:217], v[92:95]
	v_mfma_f32_16x16x32_bf16 v[88:91], v[144:147], v[214:217], v[88:91]
	v_mfma_f32_16x16x32_bf16 v[76:79], v[132:135], v[222:225], v[76:79]
	v_mfma_f32_16x16x32_bf16 v[72:75], v[144:147], v[222:225], v[72:75]
	s_setprio 0
	s_setprio 1
	v_mfma_f32_16x16x32_bf16 v[116:119], v[148:151], v[180:183], v[116:119]
	v_mfma_f32_16x16x32_bf16 v[112:115], v[156:159], v[180:183], v[112:115]
	v_mfma_f32_16x16x32_bf16 v[100:103], v[148:151], v[188:191], v[100:103]
	v_mfma_f32_16x16x32_bf16 v[96:99], v[156:159], v[188:191], v[96:99]
	v_mfma_f32_16x16x32_bf16 v[84:87], v[148:151], v[210:213], v[84:87]
	v_mfma_f32_16x16x32_bf16 v[80:83], v[156:159], v[210:213], v[80:83]
	v_mfma_f32_16x16x32_bf16 v[68:71], v[148:151], v[218:221], v[68:71]
	v_mfma_f32_16x16x32_bf16 v[64:67], v[156:159], v[218:221], v[64:67]
	v_mfma_f32_16x16x32_bf16 v[116:119], v[152:155], v[184:187], v[116:119]
	v_mfma_f32_16x16x32_bf16 v[112:115], v[160:163], v[184:187], v[112:115]
	v_mfma_f32_16x16x32_bf16 v[100:103], v[152:155], v[206:209], v[100:103]
	v_mfma_f32_16x16x32_bf16 v[96:99], v[160:163], v[206:209], v[96:99]
	v_mfma_f32_16x16x32_bf16 v[84:87], v[152:155], v[214:217], v[84:87]
	v_mfma_f32_16x16x32_bf16 v[80:83], v[160:163], v[214:217], v[80:83]
	v_mfma_f32_16x16x32_bf16 v[68:71], v[152:155], v[222:225], v[68:71]
	v_mfma_f32_16x16x32_bf16 v[64:67], v[160:163], v[222:225], v[64:67]
	s_setprio 0
	s_barrier
	s_add_i32 s6, s6, s12
	s_mov_b32 m0, s6
	ds_read_b128 v[180:183], v179 offset:16384
	ds_read_b128 v[184:187], v179 offset:17408
	ds_read_b128 v[188:191], v179 offset:18432
	ds_read_b128 v[206:209], v179 offset:19456
	ds_read_b128 v[210:213], v179 offset:20480
	ds_read_b128 v[214:217], v179 offset:21504
	ds_read_b128 v[218:221], v179 offset:22528
	ds_read_b128 v[222:225], v179 offset:23552
	global_load_lds_dwordx4 v164, s[56:57]
	s_add_i32 m0, s6, 0x2000
	s_add_u32 s6, s56, 0x2000
	s_addc_u32 s7, s57, 0
	s_add_i32 s52, s92, s12
	global_load_lds_dwordx4 v168, s[56:57]
	s_mov_b32 m0, s52
	s_nop 0
	global_load_lds_dwordx4 v164, s[6:7]
	s_add_i32 m0, s52, 0x2000
	s_nop 0
	global_load_lds_dwordx4 v168, s[6:7]
	s_mov_b32 m0, s13
	s_nop 0
	global_load_lds_dwordx4 v136, s[58:59]
	s_mov_b32 m0, s24
	s_nop 0
	global_load_lds_dwordx4 v166, s[58:59]
	s_waitcnt vmcnt(8)
	s_waitcnt lgkmcnt(0)
	s_barrier
	s_setprio 1
	s_waitcnt lgkmcnt(0)
	v_mfma_f32_16x16x32_bf16 v[60:63], v[128:131], v[180:183], v[60:63]
	v_mfma_f32_16x16x32_bf16 v[56:59], v[140:143], v[180:183], v[56:59]
	v_mfma_f32_16x16x32_bf16 v[44:47], v[128:131], v[188:191], v[44:47]
	v_mfma_f32_16x16x32_bf16 v[40:43], v[140:143], v[188:191], v[40:43]
	v_mfma_f32_16x16x32_bf16 v[28:31], v[128:131], v[210:213], v[28:31]
	v_mfma_f32_16x16x32_bf16 v[24:27], v[140:143], v[210:213], v[24:27]
	v_mfma_f32_16x16x32_bf16 v[12:15], v[128:131], v[218:221], v[12:15]
	v_mfma_f32_16x16x32_bf16 v[8:11], v[140:143], v[218:221], v[8:11]
	v_mfma_f32_16x16x32_bf16 v[60:63], v[132:135], v[184:187], v[60:63]
	v_mfma_f32_16x16x32_bf16 v[56:59], v[144:147], v[184:187], v[56:59]
	v_mfma_f32_16x16x32_bf16 v[44:47], v[132:135], v[206:209], v[44:47]
	v_mfma_f32_16x16x32_bf16 v[40:43], v[144:147], v[206:209], v[40:43]
	v_mfma_f32_16x16x32_bf16 v[28:31], v[132:135], v[214:217], v[28:31]
	v_mfma_f32_16x16x32_bf16 v[24:27], v[144:147], v[214:217], v[24:27]
	v_mfma_f32_16x16x32_bf16 v[12:15], v[132:135], v[222:225], v[12:15]
	v_mfma_f32_16x16x32_bf16 v[8:11], v[144:147], v[222:225], v[8:11]
	s_setprio 0
	s_setprio 1
	v_mfma_f32_16x16x32_bf16 v[52:55], v[148:151], v[180:183], v[52:55]
	v_mfma_f32_16x16x32_bf16 v[48:51], v[156:159], v[180:183], v[48:51]
	v_mfma_f32_16x16x32_bf16 v[36:39], v[148:151], v[188:191], v[36:39]
	v_mfma_f32_16x16x32_bf16 v[32:35], v[156:159], v[188:191], v[32:35]
	v_mfma_f32_16x16x32_bf16 v[20:23], v[148:151], v[210:213], v[20:23]
	v_mfma_f32_16x16x32_bf16 v[16:19], v[156:159], v[210:213], v[16:19]
	v_mfma_f32_16x16x32_bf16 v[4:7], v[148:151], v[218:221], v[4:7]
	v_mfma_f32_16x16x32_bf16 v[0:3], v[156:159], v[218:221], v[0:3]
	v_mfma_f32_16x16x32_bf16 v[52:55], v[152:155], v[184:187], v[52:55]
	v_mfma_f32_16x16x32_bf16 v[48:51], v[160:163], v[184:187], v[48:51]
	v_mfma_f32_16x16x32_bf16 v[36:39], v[152:155], v[206:209], v[36:39]
	v_mfma_f32_16x16x32_bf16 v[32:35], v[160:163], v[206:209], v[32:35]
	v_mfma_f32_16x16x32_bf16 v[20:23], v[152:155], v[214:217], v[20:23]
	v_mfma_f32_16x16x32_bf16 v[16:19], v[160:163], v[214:217], v[16:19]
	v_mfma_f32_16x16x32_bf16 v[4:7], v[152:155], v[222:225], v[4:7]
	v_mfma_f32_16x16x32_bf16 v[0:3], v[160:163], v[222:225], v[0:3]
	s_setprio 0
	s_barrier
; #define PG8_STAGE(bufoff, gbase, voff) do { _Pragma("unroll") for (int _i = 0; _i < 2; ++_i) \
;         __builtin_amdgcn_global_load_lds((const unsigned*)((const char*)(gbase) + (voff)[_i]), (LAS unsigned*)(lds + (bufoff) + ldsw + _i * 8192), 16, 0, 0); } while (0)
; #define PG8_LDA(dst, b, h) do { _Pragma("unroll") for (int m = 0; m < 4; ++m) _Pragma("unroll") for (int k = 0; k < 2; ++k) dst[m][k] = *(const LAS bf16x8*)(lds + PG8_SA(b, h) + aoff + m * 2048 + k * 1024); } while (0)
; #define PG8_LDB(dst, b, h) do { _Pragma("unroll") for (int n = 0; n < 2; ++n) _Pragma("unroll") for (int k = 0; k < 2; ++k) dst[n][k] = *(const LAS bf16x8*)(lds + PG8_SB(b, h) + boff + n * 2048 + k * 1024); } while (0)
; #define PG8_MMA(ai, bj, At, Bt) do { __builtin_amdgcn_s_setprio(1); _Pragma("unroll") for (int m = 0; m < 4; ++m) _Pragma("unroll") for (int n = 0; n < 2; ++n) _Pragma("unroll") for (int k = 0; k < 2; ++k) \
;         acc[ai][bj][m][n] = __builtin_amdgcn_mfma_f32_16x16x32_bf16(Bt[n][k], At[m][k], acc[ai][bj][m][n], 0, 0, 0); __builtin_amdgcn_s_setprio(0); } while (0)
; #define PG8_WAIT_V(n) asm volatile("s_waitcnt vmcnt(" #n ")" ::: "memory")
; #define PG8_WAIT_L(n) asm volatile("s_waitcnt lgkmcnt(" #n ")" ::: "memory")
; #define PG8_BAR __builtin_amdgcn_s_barrier()
; #define PG8_SCHED __builtin_amdgcn_sched_barrier(0)
; template <class Epi, bool ALIGN_EPI>
; __device__ __forceinline__ void gemm_phase(LAS unsigned char* lds, const Gemm g, int G, int cid, const Epi& E) {
;     ...
;             PG8_LDB(B0, 1, 0); PG8_LDB(B1, 1, 1); PG8_SCHED; PG8_LDA(At, 1, 0); PG8_STAGE(PG8_SA(0, 1), a2 + hA, voffA);
;             PG8_WAIT_V(8); PG8_WAIT_L(0); PG8_BAR; PG8_MMA(0, 0, At, B0); PG8_MMA(0, 1, At, B1); PG8_BAR; PG8_SCHED;
;             PG8_LDA(At, 1, 1); PG8_STAGE(PG8_SB(1, 0), b3, voffB); PG8_STAGE(PG8_SB(1, 1), b3 + hB, voffB); PG8_STAGE(PG8_SA(1, 0), a3, voffA);
;             PG8_WAIT_V(8); PG8_WAIT_L(0); PG8_BAR; PG8_MMA(1, 0, At, B0); PG8_MMA(1, 1, At, B1); PG8_BAR; PG8_SCHED;
	s_add_i32 s52, 0, 0x18000
	s_add_i32 s53, 0, 0x1c000
	v_add_u32_e32 v144, s52, v176
	v_add_u32_e32 v160, s53, v176
	ds_read_b128 v[128:131], v144
	ds_read_b128 v[132:135], v144 offset:1024
	ds_read_b128 v[140:143], v144 offset:2048
	ds_read_b128 v[144:147], v144 offset:3072
	ds_read_b128 v[148:151], v160
	ds_read_b128 v[152:155], v160 offset:1024
	ds_read_b128 v[156:159], v160 offset:2048
	ds_read_b128 v[160:163], v160 offset:3072
	s_add_u32 s6, s58, 0x84000
	s_addc_u32 s7, s59, 0
	s_mov_b32 m0, s25
	ds_read_b128 v[180:183], v179 offset:32768
	ds_read_b128 v[184:187], v179 offset:33792
	ds_read_b128 v[188:191], v179 offset:34816
	ds_read_b128 v[206:209], v179 offset:35840
	ds_read_b128 v[210:213], v179 offset:36864
	ds_read_b128 v[214:217], v179 offset:37888
	ds_read_b128 v[218:221], v179 offset:38912
	ds_read_b128 v[222:225], v179 offset:39936
	global_load_lds_dwordx4 v136, s[6:7]
	s_mov_b32 m0, s74
	s_nop 0
	global_load_lds_dwordx4 v166, s[6:7]
	s_waitcnt vmcnt(8)
	s_waitcnt lgkmcnt(0)
	s_barrier
	s_setprio 1
	s_waitcnt lgkmcnt(0)
	v_mfma_f32_16x16x32_bf16 v[124:127], v[128:131], v[180:183], v[124:127]
	v_mfma_f32_16x16x32_bf16 v[120:123], v[140:143], v[180:183], v[120:123]
	v_mfma_f32_16x16x32_bf16 v[108:111], v[128:131], v[188:191], v[108:111]
	v_mfma_f32_16x16x32_bf16 v[104:107], v[140:143], v[188:191], v[104:107]
	v_mfma_f32_16x16x32_bf16 v[92:95], v[128:131], v[210:213], v[92:95]
	v_mfma_f32_16x16x32_bf16 v[88:91], v[140:143], v[210:213], v[88:91]
	v_mfma_f32_16x16x32_bf16 v[76:79], v[128:131], v[218:221], v[76:79]
	v_mfma_f32_16x16x32_bf16 v[72:75], v[140:143], v[218:221], v[72:75]
	v_mfma_f32_16x16x32_bf16 v[124:127], v[132:135], v[184:187], v[124:127]
	v_mfma_f32_16x16x32_bf16 v[120:123], v[144:147], v[184:187], v[120:123]
	v_mfma_f32_16x16x32_bf16 v[108:111], v[132:135], v[206:209], v[108:111]
	v_mfma_f32_16x16x32_bf16 v[104:107], v[144:147], v[206:209], v[104:107]
	v_mfma_f32_16x16x32_bf16 v[92:95], v[132:135], v[214:217], v[92:95]
	v_mfma_f32_16x16x32_bf16 v[88:91], v[144:147], v[214:217], v[88:91]
	v_mfma_f32_16x16x32_bf16 v[76:79], v[132:135], v[222:225], v[76:79]
	v_mfma_f32_16x16x32_bf16 v[72:75], v[144:147], v[222:225], v[72:75]
	s_setprio 0
	s_setprio 1
	v_mfma_f32_16x16x32_bf16 v[116:119], v[148:151], v[180:183], v[116:119]
	v_mfma_f32_16x16x32_bf16 v[112:115], v[156:159], v[180:183], v[112:115]
	v_mfma_f32_16x16x32_bf16 v[100:103], v[148:151], v[188:191], v[100:103]
	v_mfma_f32_16x16x32_bf16 v[96:99], v[156:159], v[188:191], v[96:99]
	v_mfma_f32_16x16x32_bf16 v[84:87], v[148:151], v[210:213], v[84:87]
	v_mfma_f32_16x16x32_bf16 v[80:83], v[156:159], v[210:213], v[80:83]
	v_mfma_f32_16x16x32_bf16 v[68:71], v[148:151], v[218:221], v[68:71]
	v_mfma_f32_16x16x32_bf16 v[64:67], v[156:159], v[218:221], v[64:67]
	v_mfma_f32_16x16x32_bf16 v[116:119], v[152:155], v[184:187], v[116:119]
	v_mfma_f32_16x16x32_bf16 v[112:115], v[160:163], v[184:187], v[112:115]
	v_mfma_f32_16x16x32_bf16 v[100:103], v[152:155], v[206:209], v[100:103]
	v_mfma_f32_16x16x32_bf16 v[96:99], v[160:163], v[206:209], v[96:99]
	v_mfma_f32_16x16x32_bf16 v[84:87], v[152:155], v[214:217], v[84:87]
	v_mfma_f32_16x16x32_bf16 v[80:83], v[160:163], v[214:217], v[80:83]
	v_mfma_f32_16x16x32_bf16 v[68:71], v[152:155], v[222:225], v[68:71]
	v_mfma_f32_16x16x32_bf16 v[64:67], v[160:163], v[222:225], v[64:67]
	s_setprio 0
	s_barrier
	s_add_u32 s6, s56, 0x160000
	s_addc_u32 s7, s57, 0
	s_add_i32 s52, s52, s12
	s_mov_b32 m0, s52
	ds_read_b128 v[180:183], v179 offset:49152
	ds_read_b128 v[184:187], v179 offset:50176
	ds_read_b128 v[188:191], v179 offset:51200
	ds_read_b128 v[206:209], v179 offset:52224
	ds_read_b128 v[210:213], v179 offset:53248
	ds_read_b128 v[214:217], v179 offset:54272
	ds_read_b128 v[218:221], v179 offset:55296
	ds_read_b128 v[222:225], v179 offset:56320
	global_load_lds_dwordx4 v164, s[6:7]
	s_add_i32 m0, s52, 0x2000
	s_nop 0
	global_load_lds_dwordx4 v168, s[6:7]
	s_add_u32 s6, s56, 0x162000
	s_addc_u32 s7, s57, 0
	s_add_i32 s52, s53, s12
	s_mov_b32 m0, s52
	s_add_u32 vcc_lo, s58, s36
	s_addc_u32 vcc_hi, s59, s37
	global_load_lds_dwordx4 v164, s[6:7]
	s_add_i32 m0, s52, 0x2000
	s_nop 0
	global_load_lds_dwordx4 v168, s[6:7]
	s_mov_b32 m0, s75
	s_nop 0
	global_load_lds_dwordx4 v136, vcc
	s_mov_b32 m0, s76
	s_nop 0
	global_load_lds_dwordx4 v166, vcc
	s_waitcnt vmcnt(8)
	s_waitcnt lgkmcnt(0)
	s_barrier
	s_setprio 1
	s_waitcnt lgkmcnt(0)
	v_mfma_f32_16x16x32_bf16 v[60:63], v[128:131], v[180:183], v[60:63]
	v_mfma_f32_16x16x32_bf16 v[56:59], v[140:143], v[180:183], v[56:59]
	v_mfma_f32_16x16x32_bf16 v[44:47], v[128:131], v[188:191], v[44:47]
	v_mfma_f32_16x16x32_bf16 v[40:43], v[140:143], v[188:191], v[40:43]
	v_mfma_f32_16x16x32_bf16 v[28:31], v[128:131], v[210:213], v[28:31]
	v_mfma_f32_16x16x32_bf16 v[24:27], v[140:143], v[210:213], v[24:27]
	v_mfma_f32_16x16x32_bf16 v[12:15], v[128:131], v[218:221], v[12:15]
	v_mfma_f32_16x16x32_bf16 v[8:11], v[140:143], v[218:221], v[8:11]
	v_mfma_f32_16x16x32_bf16 v[60:63], v[132:135], v[184:187], v[60:63]
	v_mfma_f32_16x16x32_bf16 v[56:59], v[144:147], v[184:187], v[56:59]
	v_mfma_f32_16x16x32_bf16 v[44:47], v[132:135], v[206:209], v[44:47]
	v_mfma_f32_16x16x32_bf16 v[40:43], v[144:147], v[206:209], v[40:43]
	v_mfma_f32_16x16x32_bf16 v[28:31], v[132:135], v[214:217], v[28:31]
	v_mfma_f32_16x16x32_bf16 v[24:27], v[144:147], v[214:217], v[24:27]
	v_mfma_f32_16x16x32_bf16 v[12:15], v[132:135], v[222:225], v[12:15]
	v_mfma_f32_16x16x32_bf16 v[8:11], v[144:147], v[222:225], v[8:11]
	s_setprio 0
	s_setprio 1
	v_mfma_f32_16x16x32_bf16 v[52:55], v[148:151], v[180:183], v[52:55]
	v_mfma_f32_16x16x32_bf16 v[48:51], v[156:159], v[180:183], v[48:51]
	v_mfma_f32_16x16x32_bf16 v[36:39], v[148:151], v[188:191], v[36:39]
	v_mfma_f32_16x16x32_bf16 v[32:35], v[156:159], v[188:191], v[32:35]
	v_mfma_f32_16x16x32_bf16 v[20:23], v[148:151], v[210:213], v[20:23]
	v_mfma_f32_16x16x32_bf16 v[16:19], v[156:159], v[210:213], v[16:19]
	v_mfma_f32_16x16x32_bf16 v[4:7], v[148:151], v[218:221], v[4:7]
	v_mfma_f32_16x16x32_bf16 v[0:3], v[156:159], v[218:221], v[0:3]
	v_mfma_f32_16x16x32_bf16 v[52:55], v[152:155], v[184:187], v[52:55]
	v_mfma_f32_16x16x32_bf16 v[48:51], v[160:163], v[184:187], v[48:51]
	v_mfma_f32_16x16x32_bf16 v[36:39], v[152:155], v[206:209], v[36:39]
	v_mfma_f32_16x16x32_bf16 v[32:35], v[160:163], v[206:209], v[32:35]
	v_mfma_f32_16x16x32_bf16 v[20:23], v[152:155], v[214:217], v[20:23]
	v_mfma_f32_16x16x32_bf16 v[16:19], v[160:163], v[214:217], v[16:19]
	v_mfma_f32_16x16x32_bf16 v[4:7], v[152:155], v[222:225], v[4:7]
	v_mfma_f32_16x16x32_bf16 v[0:3], v[160:163], v[222:225], v[0:3]
	s_setprio 0
	s_barrier
	s_add_i32 s91, s91, 2
	s_add_u32 s50, s50, 0x2c0000
	s_addc_u32 s51, s51, 0
	s_cmp_gt_u32 s91, 29
	s_mov_b64 s[52:53], s[54:55]
	s_cbranch_scc1 .LBB0_816
